# NSA compressed pass 1 (masked-block path): in-body vmcnt waits for the Q fragments no longer drain the iteration's LDS-DMA prefetch
# baseline (speedup 1.0000x reference)
.LBB0_1064:
	s_and_b32 s6, s25, 15
	s_cmp_eq_u32 s6, 0
	s_cselect_b32 s6, 1, 0
	s_sub_i32 s6, s36, s6
	s_cmp_lt_i32 s37, s6
	s_cbranch_scc1 .Lp1_fast
	s_add_i32 s6, s38, 0
	v_add_u32_e32 v29, s6, v163
	ds_read_b128 v[30:33], v29
	ds_read_b128 v[34:37], v29 offset:4096
	v_add_u32_e32 v29, s6, v165
	v_add_u32_e32 v66, s6, v211
	ds_read_b128 v[46:49], v29 offset:4096
	ds_read_b128 v[50:53], v29
	s_waitcnt lgkmcnt(2)
	v_mfma_f32_16x16x32_bf16 v[42:45], v[34:37], v[14:17], 0
	ds_read_b128 v[58:61], v66 offset:4096
	ds_read_b128 v[66:69], v66
	v_add_u32_e32 v29, s6, v212
	v_add_u32_e32 v81, v0, v19
	s_nop 0
	v_mfma_f32_16x16x32_bf16 v[34:37], v[34:37], v[10:13], 0
	v_cmp_lt_i32_e32 vcc, 31, v81
	ds_read_b128 v[70:73], v29
	s_add_i32 s6, s38, 0x4000
	s_waitcnt lgkmcnt(2)
	v_mfma_f32_16x16x32_bf16 v[42:45], v[58:61], v[2:5], v[42:45]
	s_cmpk_lg_u32 s38, 0x8000
	s_cselect_b32 s38, s6, 0
	s_add_i32 s6, s12, 0x4000
	s_nop 0
	v_mfma_f32_16x16x32_bf16 v[34:37], v[58:61], v[6:9], v[34:37]
	ds_read_b128 v[58:61], v29 offset:4096
	s_nop 1
	v_cndmask_b32_e32 v82, v201, v42, vcc
	v_cmp_lt_i32_e32 vcc, 32, v81
	v_mfma_f32_16x16x32_bf16 v[54:57], v[46:49], v[14:17], 0
	v_add_u32_e32 v29, v0, v18
	v_cndmask_b32_e32 v83, v201, v43, vcc
	v_cmp_lt_i32_e32 vcc, 33, v81
	v_mfma_f32_16x16x32_bf16 v[46:49], v[46:49], v[10:13], 0
	s_cmpk_lg_u32 s12, 0x8000
	v_cndmask_b32_e32 v84, v201, v44, vcc
	v_cmp_lt_i32_e32 vcc, 34, v29
	s_waitcnt lgkmcnt(0)
	v_mfma_f32_16x16x32_bf16 v[46:49], v[58:61], v[6:9], v[46:49]
	s_cselect_b32 s12, s6, 0
	v_cndmask_b32_e32 v85, v201, v37, vcc
	v_cmp_lt_i32_e32 vcc, 34, v81
	v_mfma_f32_16x16x32_bf16 v[54:57], v[58:61], v[2:5], v[54:57]
	s_add_i32 s6, s37, 1
	v_cndmask_b32_e32 v86, v201, v45, vcc
	v_cmp_lt_i32_e32 vcc, 35, v29
	v_mfma_f32_16x16x32_bf16 v[58:61], v[50:53], v[14:17], 0
	v_subrev_u32_e32 v0, 64, v0
	v_cndmask_b32_e32 v87, v201, v46, vcc
	v_cmp_lt_i32_e32 vcc, 35, v81
	v_mfma_f32_16x16x32_bf16 v[38:41], v[30:33], v[14:17], 0
	v_lshl_add_u64 v[24:25], v[24:25], 0, s[80:81]
	v_cndmask_b32_e32 v54, v201, v54, vcc
	v_cmp_lt_i32_e32 vcc, 36, v29
	v_mfma_f32_16x16x32_bf16 v[30:33], v[30:33], v[10:13], 0
	s_cmp_lg_u32 s37, s36
	v_cndmask_b32_e32 v88, v201, v47, vcc
	v_cmp_lt_i32_e32 vcc, 36, v81
	v_mfma_f32_16x16x32_bf16 v[42:45], v[70:73], v[2:5], v[58:61]
	v_add_u32_e32 v26, 64, v26
	v_cndmask_b32_e32 v55, v201, v55, vcc
	v_cmp_lt_i32_e32 vcc, 37, v29
	v_mfma_f32_16x16x32_bf16 v[30:33], v[66:69], v[6:9], v[30:33]
	s_nop 0
	v_cndmask_b32_e32 v58, v201, v48, vcc
	v_cmp_lt_i32_e32 vcc, 37, v81
	v_mfma_f32_16x16x32_bf16 v[38:41], v[66:69], v[2:5], v[38:41]
	s_nop 0
	v_cndmask_b32_e32 v56, v201, v56, vcc
	v_cmp_lt_i32_e32 vcc, 38, v29
	s_nop 1
	v_cndmask_b32_e32 v59, v201, v49, vcc
	v_cmp_lt_i32_e32 vcc, 38, v81
	v_mfma_f32_16x16x32_bf16 v[46:49], v[50:53], v[10:13], 0
	s_nop 0
	v_cndmask_b32_e32 v57, v201, v57, vcc
	v_cmp_lt_i32_e32 vcc, 31, v29
	s_nop 1
	v_cndmask_b32_e32 v60, v201, v34, vcc
	v_cmp_lt_i32_e32 vcc, 32, v29
	s_nop 1
	v_cndmask_b32_e32 v50, v201, v35, vcc
	v_cmp_lt_i32_e32 vcc, 33, v29
	s_nop 1
	v_cndmask_b32_e32 v51, v201, v36, vcc
	v_cmp_lt_i32_e32 vcc, -1, v29
	v_mfma_f32_16x16x32_bf16 v[34:37], v[70:73], v[6:9], v[46:49]
	s_nop 0
	v_cndmask_b32_e32 v30, v201, v30, vcc
	v_cmp_lt_i32_e32 vcc, -1, v81
	s_nop 1
	v_cndmask_b32_e32 v38, v201, v38, vcc
	v_cmp_lt_i32_e32 vcc, 0, v29
	s_nop 1
	v_cndmask_b32_e32 v46, v201, v31, vcc
	v_cmp_lt_i32_e32 vcc, 0, v81
	s_nop 1
	v_cndmask_b32_e32 v39, v201, v39, vcc
	v_cmp_lt_i32_e32 vcc, 1, v29
	v_max3_f32 v31, v38, s83, v39
	s_nop 0
	v_cndmask_b32_e32 v32, v201, v32, vcc
	v_cmp_lt_i32_e32 vcc, 1, v81
	s_nop 1
	v_cndmask_b32_e32 v40, v201, v40, vcc
	v_cmp_lt_i32_e32 vcc, 2, v29
	s_nop 1
	v_cndmask_b32_e32 v47, v201, v33, vcc
	v_cmp_lt_i32_e32 vcc, 2, v81
	s_nop 1
	v_cndmask_b32_e32 v41, v201, v41, vcc
	v_cmp_lt_i32_e32 vcc, 3, v29
	v_max3_f32 v31, v31, v40, v41
	s_nop 0
	v_cndmask_b32_e32 v48, v201, v34, vcc
	v_cmp_lt_i32_e32 vcc, 3, v81
	s_nop 1
	v_cndmask_b32_e32 v42, v201, v42, vcc
	v_cmp_lt_i32_e32 vcc, 4, v29
	s_nop 1
	v_cndmask_b32_e32 v49, v201, v35, vcc
	v_cmp_lt_i32_e32 vcc, 4, v81
	s_nop 1
	v_cndmask_b32_e32 v43, v201, v43, vcc
	v_cmp_lt_i32_e32 vcc, 5, v29
	v_max3_f32 v31, v31, v42, v43
	s_nop 0
	v_cndmask_b32_e32 v36, v201, v36, vcc
	v_cmp_lt_i32_e32 vcc, 5, v81
	s_nop 1
	v_cndmask_b32_e32 v44, v201, v44, vcc
	v_cmp_lt_i32_e32 vcc, 6, v29
	s_nop 1
	v_cndmask_b32_e32 v37, v201, v37, vcc
	v_cmp_lt_i32_e32 vcc, 6, v81
	s_nop 1
	v_cndmask_b32_e32 v45, v201, v45, vcc
	v_max3_f32 v29, v31, v44, v45
	v_max3_f32 v29, v29, v82, v83
	v_max3_f32 v29, v29, v84, v86
	v_max3_f32 v29, v29, v54, v55
	v_max3_f32 v29, v29, v56, v57
	v_mov_b32_e32 v31, v29
	s_nop 1
	v_permlane16_swap_b32_e32 v29, v31
	v_max_f32_e32 v31, v31, v31
	v_max_f32_e32 v29, v29, v29
	v_max_f32_e32 v29, v29, v31
	v_mov_b32_e32 v31, v29
	s_nop 1
	v_permlane32_swap_b32_e32 v29, v31
	v_max3_f32 v81, v28, v29, v31
	v_sub_f32_e32 v33, v28, v81
	v_sub_f32_e32 v28, v38, v81
	v_exp_f32_e32 v29, v28
	v_sub_f32_e32 v28, v39, v81
	v_exp_f32_e32 v34, v28
	v_sub_f32_e32 v28, v40, v81
	v_exp_f32_e32 v52, v28
	v_sub_f32_e32 v28, v41, v81
	v_exp_f32_e32 v53, v28
	v_sub_f32_e32 v28, v42, v81
	v_exp_f32_e32 v61, v28
	v_sub_f32_e32 v28, v43, v81
	v_exp_f32_e32 v66, v28
	v_sub_f32_e32 v28, v44, v81
	v_exp_f32_e32 v67, v28
	v_sub_f32_e32 v28, v82, v81
	v_exp_f32_e32 v28, v28
	v_sub_f32_e32 v31, v45, v81
	v_cmp_lt_f32_e32 vcc, s76, v82
	v_exp_f32_e32 v68, v31
	v_sub_f32_e32 v35, v57, v81
	v_cndmask_b32_e32 v31, 0, v28, vcc
	v_sub_f32_e32 v28, v83, v81
	v_exp_f32_e32 v69, v28
	v_sub_f32_e32 v28, v84, v81
	v_exp_f32_e32 v70, v28
	v_sub_f32_e32 v28, v86, v81
	v_exp_f32_e32 v71, v28
	v_sub_f32_e32 v28, v54, v81
	v_exp_f32_e32 v72, v28
	v_sub_f32_e32 v28, v55, v81
	v_exp_f32_e32 v73, v28
	v_sub_f32_e32 v28, v56, v81
	v_exp_f32_e32 v89, v28
	v_max3_f32 v28, v30, s83, v46
	v_max3_f32 v28, v28, v32, v47
	v_max3_f32 v28, v28, v48, v49
	v_max3_f32 v28, v28, v36, v37
	v_max3_f32 v28, v28, v60, v50
	v_max3_f32 v28, v28, v51, v85
	v_max3_f32 v28, v28, v87, v88
	v_max3_f32 v28, v28, v58, v59
	v_mov_b32_e32 v82, v28
	s_nop 1
	v_permlane16_swap_b32_e32 v28, v82
	v_max_f32_e32 v82, v82, v82
	v_max_f32_e32 v28, v28, v28
	v_max_f32_e32 v28, v28, v82
	v_mov_b32_e32 v82, v28
	s_nop 1
	v_permlane32_swap_b32_e32 v28, v82
	v_max3_f32 v82, v27, v28, v82
	v_sub_f32_e32 v28, v30, v82
	v_exp_f32_e32 v28, v28
	v_cmp_lt_f32_e32 vcc, s76, v38
	v_exp_f32_e32 v90, v35
	v_sub_f32_e32 v27, v27, v82
	v_pk_add_f32 v[28:29], v[28:29], 0 op_sel_hi:[1,0]
	v_exp_f32_e32 v33, v33
	v_cndmask_b32_e32 v29, 0, v29, vcc
	v_cmp_lt_f32_e32 vcc, s76, v30
	v_sub_f32_e32 v30, v46, v82
	v_exp_f32_e32 v30, v30
	v_cndmask_b32_e32 v28, 0, v28, vcc
	v_cmp_lt_f32_e32 vcc, s76, v39
	s_nop 1
	v_cndmask_b32_e32 v35, 0, v34, vcc
	v_cmp_lt_f32_e32 vcc, s76, v46
	s_nop 1
	v_cndmask_b32_e32 v34, 0, v30, vcc
	v_sub_f32_e32 v30, v32, v82
	v_exp_f32_e32 v30, v30
	v_cmp_lt_f32_e32 vcc, s76, v40
	v_pk_add_f32 v[28:29], v[34:35], v[28:29]
	s_nop 0
	v_cndmask_b32_e32 v35, 0, v52, vcc
	v_cmp_lt_f32_e32 vcc, s76, v32
	v_sub_f32_e32 v32, v60, v82
	v_exp_f32_e32 v32, v32
	v_cndmask_b32_e32 v34, 0, v30, vcc
	v_sub_f32_e32 v30, v47, v82
	v_exp_f32_e32 v30, v30
	v_cmp_lt_f32_e32 vcc, s76, v41
	v_pk_add_f32 v[28:29], v[34:35], v[28:29]
	s_nop 0
	v_cndmask_b32_e32 v35, 0, v53, vcc
	v_cmp_lt_f32_e32 vcc, s76, v47
	s_nop 1
	v_cndmask_b32_e32 v34, 0, v30, vcc
	v_sub_f32_e32 v30, v48, v82
	v_exp_f32_e32 v30, v30
	v_cmp_lt_f32_e32 vcc, s76, v42
	v_pk_add_f32 v[28:29], v[34:35], v[28:29]
	s_nop 0
	v_cndmask_b32_e32 v35, 0, v61, vcc
	v_cmp_lt_f32_e32 vcc, s76, v48
	s_nop 1
	v_cndmask_b32_e32 v34, 0, v30, vcc
	v_sub_f32_e32 v30, v49, v82
	v_exp_f32_e32 v30, v30
	v_cmp_lt_f32_e32 vcc, s76, v43
	v_pk_add_f32 v[28:29], v[34:35], v[28:29]
	s_nop 0
	v_cndmask_b32_e32 v35, 0, v66, vcc
	v_cmp_lt_f32_e32 vcc, s76, v49
	s_nop 1
	v_cndmask_b32_e32 v34, 0, v30, vcc
	v_sub_f32_e32 v30, v36, v82
	v_exp_f32_e32 v30, v30
	v_cmp_lt_f32_e32 vcc, s76, v44
	v_pk_add_f32 v[28:29], v[34:35], v[28:29]
	s_nop 0
	v_cndmask_b32_e32 v35, 0, v67, vcc
	v_cmp_lt_f32_e32 vcc, s76, v36
	s_nop 1
	v_cndmask_b32_e32 v34, 0, v30, vcc
	v_sub_f32_e32 v30, v37, v82
	v_exp_f32_e32 v30, v30
	v_cmp_lt_f32_e32 vcc, s76, v45
	v_pk_add_f32 v[28:29], v[34:35], v[28:29]
	s_nop 0
	v_cndmask_b32_e32 v35, 0, v68, vcc
	v_cmp_lt_f32_e32 vcc, s76, v37
	s_nop 1
	v_cndmask_b32_e32 v34, 0, v30, vcc
	v_cmp_lt_f32_e32 vcc, s76, v60
	v_pk_add_f32 v[28:29], v[34:35], v[28:29]
	s_nop 0
	v_cndmask_b32_e32 v30, 0, v32, vcc
	v_pk_add_f32 v[28:29], v[30:31], v[28:29]
	v_sub_f32_e32 v30, v50, v82
	v_exp_f32_e32 v30, v30
	v_cmp_lt_f32_e32 vcc, s76, v83
	v_exp_f32_e32 v32, v27
	s_nop 0
	v_cndmask_b32_e32 v31, 0, v69, vcc
	v_cmp_lt_f32_e32 vcc, s76, v50
	s_nop 1
	v_cndmask_b32_e32 v30, 0, v30, vcc
	v_pk_add_f32 v[28:29], v[30:31], v[28:29]
	v_sub_f32_e32 v30, v51, v82
	v_exp_f32_e32 v30, v30
	v_cmp_lt_f32_e32 vcc, s76, v84
	s_nop 1
	v_cndmask_b32_e32 v31, 0, v70, vcc
	v_cmp_lt_f32_e32 vcc, s76, v51
	s_nop 1
	v_cndmask_b32_e32 v30, 0, v30, vcc
	v_pk_add_f32 v[28:29], v[30:31], v[28:29]
	v_sub_f32_e32 v30, v85, v82
	v_exp_f32_e32 v30, v30
	v_cmp_lt_f32_e32 vcc, s76, v86
	s_nop 1
	v_cndmask_b32_e32 v31, 0, v71, vcc
	v_cmp_lt_f32_e32 vcc, s76, v85
	s_nop 1
	v_cndmask_b32_e32 v30, 0, v30, vcc
	v_pk_add_f32 v[28:29], v[30:31], v[28:29]
	v_sub_f32_e32 v30, v87, v82
	v_exp_f32_e32 v30, v30
	v_cmp_lt_f32_e32 vcc, s76, v54
	s_nop 1
	v_cndmask_b32_e32 v31, 0, v72, vcc
	v_cmp_lt_f32_e32 vcc, s76, v87
	s_nop 1
	v_cndmask_b32_e32 v30, 0, v30, vcc
	v_pk_add_f32 v[28:29], v[30:31], v[28:29]
	v_sub_f32_e32 v30, v88, v82
	v_exp_f32_e32 v30, v30
	v_cmp_lt_f32_e32 vcc, s76, v55
	s_nop 1
	v_cndmask_b32_e32 v31, 0, v73, vcc
	v_cmp_lt_f32_e32 vcc, s76, v88
	s_nop 1
	v_cndmask_b32_e32 v30, 0, v30, vcc
	v_pk_add_f32 v[28:29], v[30:31], v[28:29]
	v_sub_f32_e32 v30, v58, v82
	v_exp_f32_e32 v30, v30
	v_cmp_lt_f32_e32 vcc, s76, v56
	s_nop 1
	v_cndmask_b32_e32 v31, 0, v89, vcc
	v_cmp_lt_f32_e32 vcc, s76, v58
	s_nop 1
	v_cndmask_b32_e32 v30, 0, v30, vcc
	v_pk_add_f32 v[28:29], v[30:31], v[28:29]
	v_sub_f32_e32 v30, v59, v82
	v_exp_f32_e32 v30, v30
	v_cmp_lt_f32_e32 vcc, s76, v57
	s_nop 1
	v_cndmask_b32_e32 v31, 0, v90, vcc
	v_cmp_lt_f32_e32 vcc, s76, v59
	s_nop 1
	v_cndmask_b32_e32 v30, 0, v30, vcc
	v_pk_add_f32 v[28:29], v[30:31], v[28:29]
	s_nop 0
	v_pk_fma_f32 v[20:21], v[20:21], v[32:33], v[28:29]
	s_cbranch_scc0 .LBB0_1068
	v_mov_b32_e32 v28, v81
	v_mov_b32_e32 v27, v82
	s_mov_b32 s37, s6
	s_cmp_ge_u32 s37, s36
	s_mov_b64 s[6:7], -1
	s_cbranch_scc1 .LBB0_1061
